# DQK=64 second-half staging writes wait only for the tile they store (exact vmcnt) when the next prefetch was issued
# speedup vs baseline: 1.0016x; 1.0016x over previous
; #define SBAR() __builtin_amdgcn_sched_barrier(0)
; #define SLOAD(i, k0) do { sr_[i].vs0 = GLD8(&Vh[(long)((k0) + sr) * LD + sc]); sr_[i].vs1 = GLD8(&Vh[(long)((k0) + 32 + sr) * LD + sc]); \
;     if (DQK == 128) { sr_[i].ks0 = GLD8(&Kh[(long)((k0) + sr) * LD + sc]); sr_[i].ks1 = GLD8(&Kh[(long)((k0) + 32 + sr) * LD + sc]); } \
;     else { sr_[i].ks0 = GLD8(&Kh[(long)((k0) + kr) * LD + kc]); } } while (0)
; __device__ __forceinline__ void finishSM(f32x16& p0, f32x16& p1, float alpha, float& l_reg, bf16x8& pa0, bf16x8& pa1, bf16x8& pa2, bf16x8& pa3) {
; #pragma unroll
;   for (int r = 0; r < 16; ++r) p1[r] = __builtin_amdgcn_exp2f(p1[r]);
;   float ps = 0;
; #pragma unroll
;   for (int r = 0; r < 16; ++r) ps += p0[r];
; #pragma unroll
;   for (int r = 0; r < 16; ++r) ps += p1[r];
;   { auto rr = __builtin_amdgcn_permlane32_swap(__float_as_uint(ps), __float_as_uint(ps), false, false);
;     ps = __uint_as_float(rr[0]) + __uint_as_float(rr[1]); }
;   l_reg = l_reg * alpha + ps;
;     ...
;   PK4(p0, 0, pa0); PK4(p0, 8, pa1); PK4(p1, 0, pa2); PK4(p1, 8, pa3);
;     ...
; }
; template <int DQK> __device__ __forceinline__ void qkt(f32x16& p0, f32x16& p1, const char* Ks, const bf16x8* qr, int r32, int hi, const f32x16& negm) {
; #pragma unroll
;   for (int d0 = 0; d0 < DQK / 16; ++d0) { const int cb = (d0 * 16 + hi * 8) * 2;
;     const bf16x8 b0 = *reinterpret_cast<const bf16x8*>(Ks + (DQK == 128 ? KSWZ(r32, cb) : KSWZ64(r32, cb)));
;     const bf16x8 b1 = *reinterpret_cast<const bf16x8*>(Ks + (DQK == 128 ? KSWZ(32 + r32, cb) : KSWZ64(32 + r32, cb)));
;     if (d0 == 0) { p0 = __builtin_amdgcn_mfma_f32_32x32x16_bf16(b0, qr[0], negm, 0, 0, 0); p1 = __builtin_amdgcn_mfma_f32_32x32x16_bf16(b1, qr[0], negm, 0, 0, 0); }
;     else { p0 = __builtin_amdgcn_mfma_f32_32x32x16_bf16(b0, qr[d0], p0, 0, 0, 0); p1 = __builtin_amdgcn_mfma_f32_32x32x16_bf16(b1, qr[d0], p1, 0, 0, 0); } }
; }
; template <int DQK, bool BIAS, bool VIRT = false>
; __device__ __forceinline__ void attn_pass(const bf16_t* __restrict__ Qb, const bf16_t* __restrict__ Kh, const bf16_t* __restrict__ Vh, int L, int NT, int qw0, const float* lut, f32x16 (&o)[4], char* lds, int nact) {
;     ...
;     NEGM(j + 1); SBAR(); qkt<DQK>(pA0, pA1, K_lds, qr, r32, hi, negm);
;     finishSM(pB0, pB1, alB, l_reg, pa0, pa1, pa2, pa3); SBAR();
;     if (SDEPTH == 1 || j + 3 < NT) SLOAD(SE, (j + 1 + SDEPTH) * KVBLK); SBAR();
.Lcret_f2:
	v_mfma_f32_32x32x16_bf16 v[68:83], v[100:103], v[162:165], v[236:251]
	v_mfma_f32_32x32x16_bf16 v[100:115], v[84:87], v[162:165], v[236:251]
	ds_read_b128 v[84:87], v226 offset:36864
	v_add_f32_e32 v235, 0, v219
	v_add_f32_e32 v235, v233, v235
	v_add_f32_e32 v235, v209, v235
	v_add_f32_e32 v235, v220, v235
	v_add_f32_e32 v235, v207, v235
	v_add_f32_e32 v235, v218, v235
	v_add_f32_e32 v235, v206, v235
	v_add_f32_e32 v235, v208, v235
	v_add_f32_e32 v235, v203, v235
	v_add_f32_e32 v235, v205, v235
	s_waitcnt lgkmcnt(3)
	v_mfma_f32_32x32x16_bf16 v[100:115], v[88:91], v[158:161], v[100:115]
	v_add_f32_e32 v235, v201, v235
	v_add_f32_e32 v235, v204, v235
	v_add_f32_e32 v235, v199, v235
	v_add_f32_e32 v235, v202, v235
	v_add_f32_e32 v235, v198, v235
	v_add_f32_e32 v235, v200, v235
	v_mfma_f32_32x32x16_bf16 v[68:83], v[134:137], v[158:161], v[68:83]
	ds_read_b128 v[88:91], v226 offset:32768
	v_cvt_pk_bf16_f32 v92, v219, v233
	v_cvt_pk_bf16_f32 v93, v209, v220
	v_cvt_pk_bf16_f32 v94, v207, v218
	v_cvt_pk_bf16_f32 v95, v206, v208
	v_add_co_u32_e32 v132, vcc, 0x10341000, v148
	s_waitcnt lgkmcnt(2)
	v_mfma_f32_32x32x16_bf16 v[100:115], v[138:141], v[154:157], v[100:115]
	v_cvt_pk_bf16_f32 v96, v203, v205
	v_cvt_pk_bf16_f32 v97, v201, v204
	v_addc_co_u32_e32 v133, vcc, 0, v149, vcc
	v_add_co_u32_e32 v174, vcc, 0x10389000, v148
	v_cvt_pk_bf16_f32 v98, v199, v202
	v_cvt_pk_bf16_f32 v99, v198, v200
	v_addc_co_u32_e32 v175, vcc, 0, v149, vcc
	v_mfma_f32_32x32x16_bf16 v[68:83], v[142:145], v[154:157], v[68:83]
	ds_read_b64_tr_b16 v[134:135], v211 offset:0
	ds_read_b64_tr_b16 v[136:137], v211 offset:0x800
	ds_read_b64_tr_b16 v[138:139], v211 offset:0x200
	ds_read_b64_tr_b16 v[140:141], v211 offset:0xa00
	ds_read_b64_tr_b16 v[142:143], v211 offset:0x400
	ds_read_b64_tr_b16 v[144:145], v211 offset:0xc00
	ds_read_b64_tr_b16 v[146:147], v211 offset:0x600
	ds_read_b64_tr_b16 v[148:149], v211 offset:0xe00
	v_permlane32_swap_b32_e32 v92, v94
	v_permlane32_swap_b32_e32 v93, v95
	v_add_co_u32_e32 v176, vcc, 0x10340000, v196
	s_waitcnt lgkmcnt(8)
	v_mfma_f32_32x32x16_bf16 v[100:115], v[84:87], v[150:153], v[100:115]
	v_permlane32_swap_b32_e32 v96, v98
	v_permlane32_swap_b32_e32 v97, v99
	v_mfma_f32_32x32x16_bf16 v[68:83], v[88:91], v[150:153], v[68:83]
	v_addc_co_u32_e32 v177, vcc, 0, v197, vcc
	s_mov_b32 s98, 0
	s_cmp_ge_u32 s4, s28
	s_cbranch_scc1 .Lnold_h2
	global_load_dwordx4 v[166:169], v[132:133], off
	global_load_dwordx4 v[170:173], v[174:175], off
	global_load_dwordx4 v[174:177], v[176:177], off offset:2048
	s_mov_b32 s98, 1

; #define SWRITE(b, i) do { *(bf16x8*)(V_lds + (b) * SHM_V + vst0) = sr_[i].vs0; *(bf16x8*)(V_lds + (b) * SHM_V + vst1) = sr_[i].vs1; \
;     if (DQK == 128) { *(bf16x8*)(K_lds + (b) * SHM_K + KSWZ(sr, sc * 2)) = sr_[i].ks0; *(bf16x8*)(K_lds + (b) * SHM_K + KSWZ(32 + sr, sc * 2)) = sr_[i].ks1; } \
;     else { *(bf16x8*)(K_lds + (b) * SHM_K + KSWZ64(kr, kc * 2)) = sr_[i].ks0; } } while (0)
; #define SWAIT() do { if (SDEPTH == 1) asm volatile("s_waitcnt vmcnt(0)" ::: "memory"); else if (DQK == 128) asm volatile("s_waitcnt vmcnt(4)" ::: "memory"); else asm volatile("s_waitcnt vmcnt(3)" ::: "memory"); } while (0)
; #define RESC(a) do { if (__any((a) < 1.f)) { if (hi == 0) al_l[r32] = (a); asm volatile("s_waitcnt lgkmcnt(0)" ::: "memory"); \
;     _Pragma("unroll") for (int d = 0; d < 4; ++d) _Pragma("unroll") for (int r = 0; r < 16; ++r) o[d][r] *= al_l[crow(r, hi)]; } } while (0)
; template <int DQK, bool BIAS, bool VIRT = false>
; __device__ __forceinline__ void attn_pass(const bf16_t* __restrict__ Qb, const bf16_t* __restrict__ Kh, const bf16_t* __restrict__ Vh, int L, int NT, int qw0, const float* lut, f32x16 (&o)[4], char* lds, int nact) {
;     ...
;     __syncthreads(); SWAIT(); SWRITE(1, SO);
;     RESC(alA); __syncthreads();
.LBB0_243:
	s_barrier
	s_waitcnt vmcnt(3)
	v_cmp_gt_f32_e32 vcc, 1.0, v133
	s_cmp_eq_u32 s98, 0
	s_cbranch_scc1 .Lcons_h2
	ds_write_b128 v212, v[178:181] offset:16384
	ds_write_b128 v213, v[182:185] offset:16384
	ds_write_b128 v229, v[186:189] offset:49152
.Lcons_ret_h2:
	s_cbranch_vccnz .Lresc_h2

; #define SBAR() __builtin_amdgcn_sched_barrier(0)
; #define NEGM(t) do { if (BIAS) { const float c_ = cinit<BIAS, VIRT>((t), qw0, lut); if (c_ != c_cur) { c_cur = c_; const float nm_ = c_ - m_reg; _Pragma("unroll") for (int r = 0; r < 16; ++r) negm[r] = nm_; } } } while (0)
; template <int DQK, bool BIAS, bool VIRT = false>
; __device__ __forceinline__ void attn_pass(const bf16_t* __restrict__ Qb, const bf16_t* __restrict__ Kh, const bf16_t* __restrict__ Vh, int L, int NT, int qw0, const float* lut, f32x16 (&o)[4], char* lds, int nact) {
;     ...
;     NEGM(j + 1); SBAR(); qkt<DQK>(pA0, pA1, K_lds, qr, r32, hi, negm);
.Lold_h2:
	s_mov_b32 s98, 0
	s_waitcnt lgkmcnt(0)
	v_mov_b64_e32 v[100:101], v[116:117]
	v_mov_b64_e32 v[102:103], v[118:119]
	v_mov_b64_e32 v[104:105], v[120:121]
	v_mov_b64_e32 v[106:107], v[122:123]
	v_mov_b64_e32 v[108:109], v[124:125]
	v_mov_b64_e32 v[110:111], v[126:127]
	v_mov_b64_e32 v[112:113], v[128:129]
	v_mov_b64_e32 v[114:115], v[130:131]
	s_waitcnt lgkmcnt(0)
	v_cmp_neq_f32_e32 vcc, v133, v66
	s_add_i32 s4, s25, -1
	s_cbranch_vccnz .Lcupd_h2

; #define SWRITE(b, i) do { *(bf16x8*)(V_lds + (b) * SHM_V + vst0) = sr_[i].vs0; *(bf16x8*)(V_lds + (b) * SHM_V + vst1) = sr_[i].vs1; \
;     if (DQK == 128) { *(bf16x8*)(K_lds + (b) * SHM_K + KSWZ(sr, sc * 2)) = sr_[i].ks0; *(bf16x8*)(K_lds + (b) * SHM_K + KSWZ(32 + sr, sc * 2)) = sr_[i].ks1; } \
;     else { *(bf16x8*)(K_lds + (b) * SHM_K + KSWZ64(kr, kc * 2)) = sr_[i].ks0; } } while (0)
; #define SWAIT() do { if (SDEPTH == 1) asm volatile("s_waitcnt vmcnt(0)" ::: "memory"); else if (DQK == 128) asm volatile("s_waitcnt vmcnt(4)" ::: "memory"); else asm volatile("s_waitcnt vmcnt(3)" ::: "memory"); } while (0)
; template <int DQK, bool BIAS, bool VIRT = false>
; __device__ __forceinline__ void attn_pass(const bf16_t* __restrict__ Qb, const bf16_t* __restrict__ Kh, const bf16_t* __restrict__ Vh, int L, int NT, int qw0, const float* lut, f32x16 (&o)[4], char* lds, int nact) {
;     ...
;     __syncthreads(); SWAIT(); SWRITE(1, SO);
.Lcons_h2:
	s_waitcnt vmcnt(2)
	ds_write_b128 v212, v[178:181] offset:16384
	s_waitcnt vmcnt(1)
	ds_write_b128 v213, v[182:185] offset:16384
	s_waitcnt vmcnt(0)
	ds_write_b128 v229, v[186:189] offset:49152
	s_branch .Lcons_ret_h2
